# row phase (layers 2-4): OUT-row loads issued together with the residual-row loads, and the per-row drain of the previous row's stores removed (counted waits stay valid since vmcnt is in issue order)
# speedup vs baseline: 1.0045x; 1.0027x over previous
.LBB0_435:
	v_add_u32_e32 v66, s61, v41
	s_mov_b64 s[0:1], -1
	s_and_b64 vcc, exec, s[14:15]
	s_cbranch_vccz .LBB0_438
	v_mad_i64_i32 v[0:1], s[0:1], v66, s70, v[42:43]
	global_load_dwordx2 v[2:3], v[0:1], off nt
	global_load_dwordx2 v[4:5], v[0:1], off offset:512 nt
	global_load_dwordx2 v[6:7], v[0:1], off offset:1024 nt
	global_load_dwordx2 v[8:9], v[0:1], off offset:1536 nt
	global_load_dwordx2 v[10:11], v[0:1], off offset:2048 nt
	global_load_dwordx2 v[32:33], v[0:1], off offset:2560 nt
	global_load_dwordx2 v[34:35], v[0:1], off offset:3072 nt
	global_load_dwordx2 v[68:69], v[0:1], off offset:3584 nt
	v_mad_i64_i32 v[120:121], s[0:1], v66, s70, v[62:63]
	global_load_dwordx2 v[104:105], v[120:121], off nt
	global_load_dwordx2 v[106:107], v[120:121], off offset:512 nt
	global_load_dwordx2 v[108:109], v[120:121], off offset:1024 nt
	global_load_dwordx2 v[110:111], v[120:121], off offset:1536 nt
	global_load_dwordx2 v[112:113], v[120:121], off offset:2048 nt
	global_load_dwordx2 v[114:115], v[120:121], off offset:2560 nt
	global_load_dwordx2 v[116:117], v[120:121], off offset:3072 nt
	global_load_dwordx2 v[118:119], v[120:121], off offset:3584 nt
	s_waitcnt vmcnt(15)
	v_lshlrev_b32_e32 v28, 16, v2
	v_and_b32_e32 v29, 0xffff0000, v2
	v_lshlrev_b32_e32 v30, 16, v3
	v_and_b32_e32 v31, 0xffff0000, v3
	s_waitcnt vmcnt(14)
	v_lshlrev_b32_e32 v24, 16, v4
	v_and_b32_e32 v25, 0xffff0000, v4
	v_lshlrev_b32_e32 v26, 16, v5
	v_and_b32_e32 v27, 0xffff0000, v5
	s_waitcnt vmcnt(13)
	v_lshlrev_b32_e32 v20, 16, v6
	v_and_b32_e32 v21, 0xffff0000, v6
	v_lshlrev_b32_e32 v22, 16, v7
	v_and_b32_e32 v23, 0xffff0000, v7
	s_waitcnt vmcnt(12)
	v_lshlrev_b32_e32 v16, 16, v8
	v_and_b32_e32 v17, 0xffff0000, v8
	v_lshlrev_b32_e32 v18, 16, v9
	v_and_b32_e32 v19, 0xffff0000, v9
	s_waitcnt vmcnt(11)
	v_lshlrev_b32_e32 v12, 16, v10
	v_and_b32_e32 v13, 0xffff0000, v10
	v_lshlrev_b32_e32 v14, 16, v11
	v_and_b32_e32 v15, 0xffff0000, v11
	s_waitcnt vmcnt(10)
	v_lshlrev_b32_e32 v8, 16, v32
	v_and_b32_e32 v9, 0xffff0000, v32
	v_lshlrev_b32_e32 v10, 16, v33
	v_and_b32_e32 v11, 0xffff0000, v33
	s_waitcnt vmcnt(9)
	v_lshlrev_b32_e32 v4, 16, v34
	v_and_b32_e32 v5, 0xffff0000, v34
	v_lshlrev_b32_e32 v6, 16, v35
	v_and_b32_e32 v7, 0xffff0000, v35
	s_waitcnt vmcnt(8)
	v_lshlrev_b32_e32 v0, 16, v68
	v_and_b32_e32 v1, 0xffff0000, v68
	v_lshlrev_b32_e32 v2, 16, v69
	v_and_b32_e32 v3, 0xffff0000, v69
	v_ashrrev_i32_e32 v67, 31, v66
	s_branch .Lrows_o_loaded

.LBB0_439:
	v_add_u32_e32 v0, 0xfffff000, v66
	v_cmp_gt_i32_e32 vcc, s68, v66
	v_mov_b32_e32 v2, s19
	v_mov_b32_e32 v3, s17
	v_cndmask_b32_e32 v1, 0, v67, vcc
	v_cndmask_b32_e32 v0, v0, v66, vcc
	v_cndmask_b32_e32 v3, v2, v3, vcc
	v_mov_b32_e32 v2, s18
	v_mov_b32_e32 v4, s16
	v_cndmask_b32_e32 v2, v2, v4, vcc
	v_lshlrev_b64 v[0:1], 13, v[0:1]
	v_lshl_add_u64 v[0:1], v[2:3], 0, v[0:1]
	v_lshlrev_b32_e32 v144, 2, v38
	v_lshl_add_u64 v[0:1], v[0:1], 0, v[144:145]
	global_load_dwordx4 v[28:31], v[0:1], off nt
	global_load_dwordx4 v[24:27], v[0:1], off offset:1024 nt
	global_load_dwordx4 v[20:23], v[0:1], off offset:2048 nt
	global_load_dwordx4 v[16:19], v[0:1], off offset:3072 nt
	v_add_co_u32_e32 v0, vcc, s68, v0
	s_nop 1
	v_addc_co_u32_e32 v1, vcc, 0, v1, vcc
	global_load_dwordx4 v[12:15], v[0:1], off nt
	global_load_dwordx4 v[8:11], v[0:1], off offset:1024 nt
	global_load_dwordx4 v[4:7], v[0:1], off offset:2048 nt
	s_nop 0
	global_load_dwordx4 v[0:3], v[0:1], off offset:3072 nt
	s_and_b64 vcc, exec, s[38:39]
	s_cbranch_vccnz .LBB0_472

.Lrows_o_loaded:
	s_waitcnt vmcnt(7)
	v_mov_b64_e32 v[34:35], v[104:105]
	s_waitcnt vmcnt(6)
	v_mov_b64_e32 v[70:71], v[106:107]
	v_lshlrev_b32_e32 v144, 1, v38
	v_and_b32_e32 v33, 0xffff0000, v34
	v_and_b32_e32 v95, 0xffff0000, v70
	v_lshlrev_b32_e32 v32, 16, v34
	v_mul_f32_e32 v72, v33, v33
	v_lshlrev_b32_e32 v94, 16, v70
	v_mul_f32_e32 v70, v95, v95
	v_lshlrev_b32_e32 v34, 16, v35
	v_fmac_f32_e32 v72, v32, v32
	v_lshlrev_b32_e32 v92, 16, v71
	v_fmac_f32_e32 v70, v94, v94
	v_and_b32_e32 v35, 0xffff0000, v35
	v_fmac_f32_e32 v72, v34, v34
	v_and_b32_e32 v93, 0xffff0000, v71
	v_fmac_f32_e32 v70, v92, v92
	v_fmac_f32_e32 v72, v35, v35
	v_fmac_f32_e32 v70, v93, v93
	v_add_f32_e32 v72, v72, v70
	s_waitcnt vmcnt(5)
	v_mov_b64_e32 v[70:71], v[108:109]
	v_and_b32_e32 v91, 0xffff0000, v70
	v_lshlrev_b32_e32 v90, 16, v70
	v_mul_f32_e32 v70, v91, v91
	v_lshlrev_b32_e32 v88, 16, v71
	v_fmac_f32_e32 v70, v90, v90
	v_and_b32_e32 v89, 0xffff0000, v71
	v_fmac_f32_e32 v70, v88, v88
	v_fmac_f32_e32 v70, v89, v89
	v_add_f32_e32 v72, v72, v70
	s_waitcnt vmcnt(4)
	v_mov_b64_e32 v[70:71], v[110:111]
	v_and_b32_e32 v87, 0xffff0000, v70
	v_lshlrev_b32_e32 v86, 16, v70
	v_mul_f32_e32 v70, v87, v87
	v_lshlrev_b32_e32 v84, 16, v71
	v_fmac_f32_e32 v70, v86, v86
	v_and_b32_e32 v85, 0xffff0000, v71
	v_fmac_f32_e32 v70, v84, v84
	v_fmac_f32_e32 v70, v85, v85
	v_add_f32_e32 v74, v72, v70
	s_waitcnt vmcnt(3)
	v_mov_b64_e32 v[70:71], v[112:113]
	s_waitcnt vmcnt(2)
	v_mov_b64_e32 v[72:73], v[114:115]
	v_and_b32_e32 v82, 0xffff0000, v70
	v_lshlrev_b32_e32 v81, 16, v72
	v_and_b32_e32 v83, 0xffff0000, v72
	v_lshlrev_b32_e32 v79, 16, v73
	v_and_b32_e32 v77, 0xffff0000, v73
	s_waitcnt vmcnt(1)
	v_mov_b64_e32 v[96:97], v[116:117]
	s_waitcnt vmcnt(0)
	v_mov_b64_e32 v[72:73], v[118:119]
	v_lshlrev_b32_e32 v80, 16, v70
	v_lshlrev_b32_e32 v78, 16, v71
	v_and_b32_e32 v76, 0xffff0000, v71
	v_pk_mul_f32 v[70:71], v[82:83], v[82:83]
	v_and_b32_e32 v68, 0xffff0000, v96
	v_pk_fma_f32 v[70:71], v[80:81], v[80:81], v[70:71]
	v_and_b32_e32 v69, 0xffff0000, v72
	v_pk_fma_f32 v[70:71], v[78:79], v[78:79], v[70:71]
	v_lshlrev_b32_e32 v75, 16, v73
	v_pk_fma_f32 v[70:71], v[76:77], v[76:77], v[70:71]
	v_and_b32_e32 v73, 0xffff0000, v73
	v_add_f32_e32 v70, v74, v70
	v_add_f32_e32 v98, v70, v71
	v_lshlrev_b32_e32 v71, 16, v72
	v_lshlrev_b32_e32 v70, 16, v96
	v_lshlrev_b32_e32 v74, 16, v97
	v_and_b32_e32 v72, 0xffff0000, v97
	v_pk_mul_f32 v[96:97], v[68:69], v[68:69]
	s_nop 0
	v_pk_fma_f32 v[96:97], v[70:71], v[70:71], v[96:97]
	s_nop 0
	v_pk_fma_f32 v[96:97], v[74:75], v[74:75], v[96:97]
	s_nop 0
	v_pk_fma_f32 v[96:97], v[72:73], v[72:73], v[96:97]
	s_nop 0
	v_add_f32_e32 v96, v98, v96
	v_add_f32_e32 v96, v96, v97
	v_and_b32_e32 v97, 64, v181
	v_add_u32_e32 v97, 64, v97
	v_xor_b32_e32 v98, 32, v181
	v_cmp_lt_i32_e32 vcc, v98, v97
	s_nop 1
	v_cndmask_b32_e32 v98, v181, v98, vcc
	v_lshlrev_b32_e32 v98, 2, v98
	ds_bpermute_b32 v98, v98, v96
	s_waitcnt lgkmcnt(0)
	v_add_f32_e32 v96, v96, v98
	v_xor_b32_e32 v98, 16, v181
	v_cmp_lt_i32_e32 vcc, v98, v97
	s_nop 1
	v_cndmask_b32_e32 v98, v181, v98, vcc
	v_lshlrev_b32_e32 v98, 2, v98
	ds_bpermute_b32 v98, v98, v96
	s_waitcnt lgkmcnt(0)
	v_add_f32_e32 v96, v96, v98
	v_xor_b32_e32 v98, 8, v181
	v_cmp_lt_i32_e32 vcc, v98, v97
	s_nop 1
	v_cndmask_b32_e32 v98, v181, v98, vcc
	v_lshlrev_b32_e32 v98, 2, v98
	ds_bpermute_b32 v98, v98, v96
	s_waitcnt lgkmcnt(0)
	v_add_f32_e32 v96, v96, v98
	v_xor_b32_e32 v98, 4, v181
	v_cmp_lt_i32_e32 vcc, v98, v97
	s_nop 1
	v_cndmask_b32_e32 v98, v181, v98, vcc
	v_lshlrev_b32_e32 v98, 2, v98
	ds_bpermute_b32 v98, v98, v96
	s_waitcnt lgkmcnt(0)
	v_add_f32_e32 v96, v96, v98
	v_xor_b32_e32 v98, 2, v181
	v_cmp_lt_i32_e32 vcc, v98, v97
	s_nop 1
	v_cndmask_b32_e32 v98, v181, v98, vcc
	v_lshlrev_b32_e32 v98, 2, v98
	ds_bpermute_b32 v98, v98, v96
	s_waitcnt lgkmcnt(0)
	v_add_f32_e32 v96, v96, v98
	v_xor_b32_e32 v98, 1, v181
	v_cmp_lt_i32_e32 vcc, v98, v97
	s_nop 1
	v_cndmask_b32_e32 v97, v181, v98, vcc
	v_lshlrev_b32_e32 v97, 2, v97
	ds_bpermute_b32 v97, v97, v96
	ds_read_b128 v[98:101], v40
	s_waitcnt lgkmcnt(1)
	v_add_f32_e32 v96, v96, v97
	v_fmamk_f32 v96, v96, 0x3a000000, v176
	v_cmp_gt_f32_e32 vcc, s72, v96
	v_mul_f32_e32 v97, 0x4b800000, v96
	s_nop 0
	v_cndmask_b32_e32 v96, v96, v97, vcc
	v_rsq_f32_e32 v96, v96
	s_nop 0
	v_mul_f32_e32 v97, 0x45800000, v96
	v_cndmask_b32_e32 v96, v96, v97, vcc
	v_pk_mul_f32 v[32:33], v[32:33], v[96:97] op_sel_hi:[1,0]
	v_pk_mul_f32 v[34:35], v[34:35], v[96:97] op_sel_hi:[1,0]
	s_waitcnt lgkmcnt(0)
	v_pk_fma_f32 v[32:33], v[98:99], v[32:33], v[28:29]
	v_mov_b64_e32 v[28:29], s[2:3]
	v_pk_fma_f32 v[34:35], v[100:101], v[34:35], v[30:31]
	v_mad_i64_i32 v[98:99], s[0:1], v66, s70, v[28:29]
	s_mov_b64 s[0:1], -1
	s_and_b64 vcc, exec, s[36:37]
	v_mov_b32_e32 v31, v35
	v_mov_b32_e32 v30, v34
	v_mov_b32_e32 v29, v33
	v_mov_b32_e32 v28, v32
	s_cbranch_vccz .LBB0_442
	v_cvt_pk_bf16_f32 v30, v32, v33
	v_cvt_pk_bf16_f32 v31, v34, v35
	v_lshl_add_u64 v[28:29], v[98:99], 0, v[144:145]
	global_store_dwordx2 v[28:29], v[30:31], off
	v_lshlrev_b32_e32 v28, 16, v30
	v_and_b32_e32 v29, 0xffff0000, v30
	v_lshlrev_b32_e32 v30, 16, v31
	v_and_b32_e32 v31, 0xffff0000, v31
	s_mov_b64 s[0:1], 0
